# e31+e29: role priorities (A 0 / B 2) plus B-loop rescale test with both alpha words read up front
# baseline (speedup 1.0000x reference)
; __device__ __forceinline__ int crow(int r, int hi) { return (r & 3) + 8 * (r >> 2) + 4 * hi; }
; __device__ __forceinline__ int crow(int r, int hi) { return (r & 3) + 8 * (r >> 2) + 4 * hi; }
; #define DMA_K(j_, b_) do { const char* kb_ = (const char*)Kh + (size_t)(j_) * (64 * LD * 2); _Pragma("unroll") for (int i = 0; i < 4; ++i) \
;     __builtin_amdgcn_global_load_lds((const unsigned*)(kb_ + kgo[i]), (LAS unsigned*)(K_las + (b_) * 16384 + (4 * a + i) * 1024), 16, 0, 0); } while (0)
; #define DMA_V(j_, b_) do { const char* vb_ = (const char*)Vh + (size_t)(j_) * (64 * LD * 2); _Pragma("unroll") for (int hf = 0; hf < 2; ++hf) _Pragma("unroll") for (int i = 0; i < 4; ++i) \
;     __builtin_amdgcn_global_load_lds((const unsigned*)(vb_ + hf * 256 + vgo[i]), (LAS unsigned*)(V_las + (b_) * 32768 + hf * 16384 + (4 * a + i) * 1024), 16, 0, 0); } while (0)
; __device__ __forceinline__ void attn_unit2(const bf16* __restrict__ Qb, const bf16* __restrict__ Kh, const bf16* __restrict__ Vh, bf16* __restrict__ Ob,
;                                            int NT, int lim, int qrow0, const float* lut, char* lds, float* scr) {
;     ...
;       if (j + 1 < NT) DMA_K(j + 1, (j + 1) & 1);
;       if (j < NT) DMA_V(j, j & 1);
;       if (j >= 1) {
;         const float* al = al0 + ((j - 1) & 1) * 128;
;         if (__any(al[r32] < 1.f) || __any(al[32 + r32] < 1.f)) {
; #pragma unroll
;           for (int rb = 0; rb < 2; ++rb)
; #pragma unroll
;             for (int d = 0; d < 4; ++d)
; #pragma unroll
;               for (int r = 0; r < 16; ++r) o[rb][d][r] *= al[rb * 32 + crow(r, hi)]; }
.LBB0_433:
	s_and_b32 s14, s10, 1
	s_lshl_b32 s15, s14, 9
	s_add_i32 s15, s4, s15
	v_lshl_add_u32 v177, v172, 2, s15
	ds_read_b32 v200, v177
	ds_read_b32 v201, v177 offset:128
	s_and_b32 s23, s9, 0x8000
	s_add_i32 s23, s6, s23
	v_lshl_add_u64 v[156:157], v[138:139], 0, s[36:37]
	s_add_i32 m0, s23, 0x8000
	v_lshl_add_u64 v[158:159], v[156:157], 0, s[54:55]
	global_load_lds_dwordx4 v[158:159], off
	v_lshl_add_u64 v[158:159], v[142:143], 0, s[36:37]
	s_nop 0
	v_lshl_add_u64 v[164:165], v[158:159], 0, s[54:55]
	s_add_i32 m0, s23, 0x8400
	v_lshl_add_u64 v[156:157], v[156:157], 0, s[68:69]
	global_load_lds_dwordx4 v[164:165], off
	v_lshl_add_u64 v[164:165], v[144:145], 0, s[36:37]
	v_lshl_add_u64 v[178:179], v[164:165], 0, s[54:55]
	s_add_i32 m0, s23, 0x8800
	s_nop 0
	s_nop 0
	global_load_lds_dwordx4 v[178:179], off
	v_lshl_add_u64 v[178:179], v[146:147], 0, s[36:37]
	v_lshl_add_u64 v[180:181], v[178:179], 0, s[54:55]
	s_add_i32 m0, s23, 0x8c00
	s_nop 0
	global_load_lds_dwordx4 v[180:181], off
	v_lshl_add_u64 v[158:159], v[158:159], 0, s[68:69]
	v_lshl_add_u64 v[164:165], v[164:165], 0, s[68:69]
	s_nop 0
	v_lshl_add_u64 v[252:253], v[178:179], 0, s[68:69]
	s_waitcnt lgkmcnt(0)
	v_cmp_gt_f32_e32 vcc, 1.0, v200
	v_cmp_gt_f32_e64 s[46:47], 1.0, v201
	s_or_b64 vcc, vcc, s[46:47]
	s_cbranch_vccz .LBB0_436
.LBB0_435:
	v_add_u32_e32 v201, s15, v140
	ds_read_b128 v[178:181], v201
	ds_read_b128 v[182:185], v201 offset:32
	ds_read_b128 v[186:189], v201 offset:64
	s_nop 0
	ds_read_b128 v[190:193], v201 offset:96
	s_waitcnt lgkmcnt(0)
	v_pk_mul_f32 v[118:119], v[118:119], v[180:181]
	v_pk_mul_f32 v[120:121], v[120:121], v[182:183]
	v_pk_mul_f32 v[124:125], v[124:125], v[186:187]
	v_pk_mul_f32 v[128:129], v[128:129], v[190:191]
	v_pk_mul_f32 v[130:131], v[130:131], v[192:193]
	v_pk_mul_f32 v[126:127], v[126:127], v[188:189]
	s_nop 0
	v_pk_mul_f32 v[122:123], v[122:123], v[184:185]
	v_pk_mul_f32 v[116:117], v[116:117], v[178:179]
	v_pk_mul_f32 v[112:113], v[112:113], v[190:191]
	v_pk_mul_f32 v[108:109], v[108:109], v[186:187]
	v_pk_mul_f32 v[104:105], v[104:105], v[182:183]
	v_pk_mul_f32 v[114:115], v[114:115], v[192:193]
	v_pk_mul_f32 v[110:111], v[110:111], v[188:189]
	v_pk_mul_f32 v[106:107], v[106:107], v[184:185]
	v_pk_mul_f32 v[102:103], v[102:103], v[180:181]
	v_pk_mul_f32 v[100:101], v[100:101], v[178:179]
	v_pk_mul_f32 v[96:97], v[96:97], v[190:191]
	v_pk_mul_f32 v[92:93], v[92:93], v[186:187]
	v_pk_mul_f32 v[88:89], v[88:89], v[182:183]
	v_pk_mul_f32 v[98:99], v[98:99], v[192:193]
	v_pk_mul_f32 v[94:95], v[94:95], v[188:189]
	v_pk_mul_f32 v[90:91], v[90:91], v[184:185]
	v_pk_mul_f32 v[86:87], v[86:87], v[180:181]
	v_pk_mul_f32 v[84:85], v[84:85], v[178:179]
	v_pk_mul_f32 v[80:81], v[80:81], v[190:191]
	v_pk_mul_f32 v[76:77], v[76:77], v[186:187]
	v_pk_mul_f32 v[72:73], v[72:73], v[182:183]
	v_pk_mul_f32 v[82:83], v[82:83], v[192:193]
	v_pk_mul_f32 v[78:79], v[78:79], v[188:189]
	v_pk_mul_f32 v[74:75], v[74:75], v[184:185]
	v_pk_mul_f32 v[70:71], v[70:71], v[180:181]
	v_pk_mul_f32 v[68:69], v[68:69], v[178:179]
	ds_read_b128 v[178:181], v201 offset:128
	ds_read_b128 v[182:185], v201 offset:160
	ds_read_b128 v[186:189], v201 offset:192
	ds_read_b128 v[190:193], v201 offset:224
	s_waitcnt lgkmcnt(0)
	v_pk_mul_f32 v[54:55], v[54:55], v[180:181]
	s_nop 0
	v_pk_mul_f32 v[56:57], v[56:57], v[182:183]
	v_pk_mul_f32 v[60:61], v[60:61], v[186:187]
	v_pk_mul_f32 v[64:65], v[64:65], v[190:191]
	v_pk_mul_f32 v[66:67], v[66:67], v[192:193]
	v_pk_mul_f32 v[62:63], v[62:63], v[188:189]
	v_pk_mul_f32 v[58:59], v[58:59], v[184:185]
	v_pk_mul_f32 v[52:53], v[52:53], v[178:179]
	v_pk_mul_f32 v[48:49], v[48:49], v[190:191]
	v_pk_mul_f32 v[44:45], v[44:45], v[186:187]
	v_pk_mul_f32 v[40:41], v[40:41], v[182:183]
	v_pk_mul_f32 v[50:51], v[50:51], v[192:193]
	v_pk_mul_f32 v[46:47], v[46:47], v[188:189]
	v_pk_mul_f32 v[42:43], v[42:43], v[184:185]
	v_pk_mul_f32 v[38:39], v[38:39], v[180:181]
	v_pk_mul_f32 v[36:37], v[36:37], v[178:179]
	v_pk_mul_f32 v[32:33], v[32:33], v[190:191]
	v_pk_mul_f32 v[28:29], v[28:29], v[186:187]
	v_pk_mul_f32 v[24:25], v[24:25], v[182:183]
	v_pk_mul_f32 v[34:35], v[34:35], v[192:193]
	v_pk_mul_f32 v[30:31], v[30:31], v[188:189]
	v_pk_mul_f32 v[26:27], v[26:27], v[184:185]
	v_pk_mul_f32 v[22:23], v[22:23], v[180:181]
	v_pk_mul_f32 v[20:21], v[20:21], v[178:179]
	v_pk_mul_f32 v[16:17], v[16:17], v[190:191]
	v_pk_mul_f32 v[12:13], v[12:13], v[186:187]
	v_pk_mul_f32 v[8:9], v[8:9], v[182:183]
	v_pk_mul_f32 v[18:19], v[18:19], v[192:193]
	v_pk_mul_f32 v[14:15], v[14:15], v[188:189]
	v_pk_mul_f32 v[10:11], v[10:11], v[184:185]
	v_pk_mul_f32 v[6:7], v[6:7], v[180:181]
	v_pk_mul_f32 v[4:5], v[4:5], v[178:179]
; #define SBAR() __builtin_amdgcn_sched_barrier(0)
; #define VRD(D0, L) const s16x4 L##0 = tr_read<v_rd_off(D0, 0, 0)>(vb), L##1 = tr_read<v_rd_off(D0, 0, 1)>(vb), L##2 = tr_read<v_rd_off(D0, 1, 0)>(vb), L##3 = tr_read<v_rd_off(D0, 1, 1)>(vb), \
;                          L##4 = tr_read<v_rd_off(D0, 2, 0)>(vb), L##5 = tr_read<v_rd_off(D0, 2, 1)>(vb), L##6 = tr_read<v_rd_off(D0, 3, 0)>(vb), L##7 = tr_read<v_rd_off(D0, 3, 1)>(vb)
; __device__ __forceinline__ void pv_four(f32x16 (&o)[2][4], int vb, bf16x8 pa0, bf16x8 pa1, bf16x8 pa2, bf16x8 pa3, bf16x8 pb0, bf16x8 pb1, bf16x8 pb2, bf16x8 pb3) {
;     ...
;   VRD(0, x); SBAR();
;   VRD(1, y); asm volatile("s_waitcnt lgkmcnt(8)" ::: "memory"); SBAR(); MMA(0, x); SBAR();
;   VRD(2, z); asm volatile("s_waitcnt lgkmcnt(8)" ::: "memory"); SBAR(); MMA(1, y); SBAR();
;   VRD(3, w); asm volatile("s_waitcnt lgkmcnt(8)" ::: "memory"); SBAR(); MMA(2, z); SBAR();
;   asm volatile("s_waitcnt lgkmcnt(0)" ::: "memory"); SBAR(); MMA(3, w);
; __device__ __forceinline__ void attn_unit2(const bf16* __restrict__ Qb, const bf16* __restrict__ Kh, const bf16* __restrict__ Vh, bf16* __restrict__ Ob,
;                                            int NT, int lim, int qrow0, const float* lut, char* lds, float* scr) {
;     ...
;         const char* ps = P0 + ((j - 1) & 1) * 16384 + lane * 16;
;         const bf16x8 pa0 = *(const bf16x8*)(ps), pa1 = *(const bf16x8*)(ps + 1024), pa2 = *(const bf16x8*)(ps + 2048), pa3 = *(const bf16x8*)(ps + 3072);
;         const bf16x8 pb0 = *(const bf16x8*)(ps + 4096), pb1 = *(const bf16x8*)(ps + 4096 + 1024), pb2 = *(const bf16x8*)(ps + 4096 + 2048), pb3 = *(const bf16x8*)(ps + 4096 + 3072);
;         const int vb = vrb + ((j - 1) & 1) * 32768 + ch * 16384;
;         pv_four(o, vb, pa0, pa1, pa2, pa3, pb0, pb1, pb2, pb3);
;       }
;       asm volatile("s_waitcnt vmcnt(0)" ::: "memory");
;       __syncthreads();
.LBB0_436:
	v_lshl_add_u32 v201, s14, 14, v175
	ds_read_b128 v[178:181], v201
	ds_read_b128 v[182:185], v201 offset:1024
	ds_read_b128 v[186:189], v201 offset:2048
	ds_read_b128 v[190:193], v201 offset:3072
	ds_read_b128 v[194:197], v201 offset:4096
	ds_read_b128 v[208:211], v201 offset:5120
	ds_read_b128 v[212:215], v201 offset:6144
	ds_read_b128 v[216:219], v201 offset:7168
	v_lshl_add_u32 v207, s14, 15, v176
	ds_read_b64_tr_b16 v[220:221], v207 offset:0
	ds_read_b64_tr_b16 v[222:223], v207 offset:0x800
	ds_read_b64_tr_b16 v[224:225], v207 offset:0x1000
	ds_read_b64_tr_b16 v[226:227], v207 offset:0x1800
	ds_read_b64_tr_b16 v[228:229], v207 offset:0x2000
	ds_read_b64_tr_b16 v[230:231], v207 offset:0x2800
	ds_read_b64_tr_b16 v[232:233], v207 offset:0x3000
	ds_read_b64_tr_b16 v[234:235], v207 offset:0x3800
	ds_read_b64_tr_b16 v[236:237], v207 offset:0x200
	ds_read_b64_tr_b16 v[238:239], v207 offset:0xa00
	ds_read_b64_tr_b16 v[240:241], v207 offset:0x1200
	ds_read_b64_tr_b16 v[242:243], v207 offset:0x1a00
	ds_read_b64_tr_b16 v[244:245], v207 offset:0x2200
	ds_read_b64_tr_b16 v[246:247], v207 offset:0x2a00
	ds_read_b64_tr_b16 v[248:249], v207 offset:0x3200
	ds_read_b64_tr_b16 v[250:251], v207 offset:0x3a00
	s_add_i32 m0, s23, 0xc000
	s_nop 0
	global_load_lds_dwordx4 v[156:157], off
	s_add_i32 m0, s23, 0xc400
	s_nop 0
	global_load_lds_dwordx4 v[158:159], off
	s_add_i32 m0, s23, 0xc800
	s_nop 0
	s_nop 0
	global_load_lds_dwordx4 v[164:165], off
	s_add_i32 m0, s23, 0xcc00
	s_nop 0
	global_load_lds_dwordx4 v[252:253], off
	s_waitcnt lgkmcnt(8)
	s_waitcnt lgkmcnt(0)
	v_mfma_f32_32x32x16_bf16 v[116:131], v[178:181], v[220:223], v[116:131]
	v_mfma_f32_32x32x16_bf16 v[52:67], v[194:197], v[220:223], v[52:67]
	v_mfma_f32_32x32x16_bf16 v[116:131], v[182:185], v[224:227], v[116:131]
	s_nop 0
	v_mfma_f32_32x32x16_bf16 v[52:67], v[208:211], v[224:227], v[52:67]
	v_mfma_f32_32x32x16_bf16 v[116:131], v[186:189], v[228:231], v[116:131]
	v_mfma_f32_32x32x16_bf16 v[52:67], v[212:215], v[228:231], v[52:67]
	v_mfma_f32_32x32x16_bf16 v[116:131], v[190:193], v[232:235], v[116:131]
	v_mfma_f32_32x32x16_bf16 v[52:67], v[216:219], v[232:235], v[52:67]
	ds_read_b64_tr_b16 v[220:221], v207 offset:0x400
	ds_read_b64_tr_b16 v[222:223], v207 offset:0xc00
	ds_read_b64_tr_b16 v[224:225], v207 offset:0x1400
	ds_read_b64_tr_b16 v[226:227], v207 offset:0x1c00
	ds_read_b64_tr_b16 v[228:229], v207 offset:0x2400
	ds_read_b64_tr_b16 v[230:231], v207 offset:0x2c00
	ds_read_b64_tr_b16 v[232:233], v207 offset:0x3400
	ds_read_b64_tr_b16 v[234:235], v207 offset:0x3c00
	s_waitcnt lgkmcnt(8)
	v_mfma_f32_32x32x16_bf16 v[100:115], v[178:181], v[236:239], v[100:115]
	v_mfma_f32_32x32x16_bf16 v[36:51], v[194:197], v[236:239], v[36:51]
	s_nop 0
	v_mfma_f32_32x32x16_bf16 v[100:115], v[182:185], v[240:243], v[100:115]
	v_mfma_f32_32x32x16_bf16 v[36:51], v[208:211], v[240:243], v[36:51]
	v_mfma_f32_32x32x16_bf16 v[100:115], v[186:189], v[244:247], v[100:115]
	v_mfma_f32_32x32x16_bf16 v[36:51], v[212:215], v[244:247], v[36:51]
	v_mfma_f32_32x32x16_bf16 v[100:115], v[190:193], v[248:251], v[100:115]
	v_mfma_f32_32x32x16_bf16 v[36:51], v[216:219], v[248:251], v[36:51]
	ds_read_b64_tr_b16 v[236:237], v207 offset:0x600
	ds_read_b64_tr_b16 v[238:239], v207 offset:0xe00
	ds_read_b64_tr_b16 v[240:241], v207 offset:0x1600
	ds_read_b64_tr_b16 v[242:243], v207 offset:0x1e00
	ds_read_b64_tr_b16 v[244:245], v207 offset:0x2600
	ds_read_b64_tr_b16 v[246:247], v207 offset:0x2e00
	ds_read_b64_tr_b16 v[248:249], v207 offset:0x3600
	ds_read_b64_tr_b16 v[250:251], v207 offset:0x3e00
	s_waitcnt lgkmcnt(8)
	v_mfma_f32_32x32x16_bf16 v[84:99], v[178:181], v[220:223], v[84:99]
	s_nop 0
	v_mfma_f32_32x32x16_bf16 v[20:35], v[194:197], v[220:223], v[20:35]
	v_mfma_f32_32x32x16_bf16 v[84:99], v[182:185], v[224:227], v[84:99]
	v_mfma_f32_32x32x16_bf16 v[20:35], v[208:211], v[224:227], v[20:35]
	v_mfma_f32_32x32x16_bf16 v[84:99], v[186:189], v[228:231], v[84:99]
	v_mfma_f32_32x32x16_bf16 v[20:35], v[212:215], v[228:231], v[20:35]
	v_mfma_f32_32x32x16_bf16 v[84:99], v[190:193], v[232:235], v[84:99]
	v_mfma_f32_32x32x16_bf16 v[20:35], v[216:219], v[232:235], v[20:35]
	s_waitcnt lgkmcnt(0)
	s_nop 0
	v_mfma_f32_32x32x16_bf16 v[68:83], v[178:181], v[236:239], v[68:83]
	s_add_i32 s9, s9, 0x8000
	s_waitcnt vmcnt(0)
	s_add_u32 s36, s36, 0x40000
	s_addc_u32 s37, s37, 0
	s_add_i32 s14, s10, 1
	s_addk_i32 s7, 0x4000
	s_cmp_eq_u32 s8, s36
	v_mfma_f32_32x32x16_bf16 v[4:19], v[194:197], v[236:239], v[4:19]
	s_waitcnt vmcnt(0)
	s_barrier
	s_nop 0
	v_mfma_f32_32x32x16_bf16 v[68:83], v[182:185], v[240:243], v[68:83]
	v_mfma_f32_32x32x16_bf16 v[4:19], v[208:211], v[240:243], v[4:19]
	v_mfma_f32_32x32x16_bf16 v[68:83], v[186:189], v[244:247], v[68:83]
	v_mfma_f32_32x32x16_bf16 v[4:19], v[212:215], v[244:247], v[4:19]
	v_mfma_f32_32x32x16_bf16 v[68:83], v[190:193], v[248:251], v[68:83]
	v_mfma_f32_32x32x16_bf16 v[4:19], v[216:219], v[248:251], v[4:19]
	s_cbranch_scc1 .LBB0_439
	s_mov_b32 s10, s14
	s_cmp_lt_u32 s10, s5
	s_cselect_b64 s[38:39], -1, 0
	s_cmp_ge_u32 s10, s5
	s_cbranch_scc0 .LBB0_432
	s_branch .LBB0_433
	s_nop 0
